# P2/P3 (two waves per SIMD, no setprio of their own): one static s_setprio 1 for waves 4-7 at P2 entry
# speedup vs baseline: 1.0041x; 1.0041x over previous
; #define LAS __attribute__((address_space(3)))
; __device__ __forceinline__ void na_strip(const Params& P, LAS unsigned char* lds, int strip, int hsel, int tid, int lane, int wave) {
;     ...
;     if (strip < 512) { sq0 = (strip >> 5) * 4096; h = (strip >> 2) & 7; r0 = (strip & 3) * 16; rows = 64; }
;     else { const int v = strip - 512; sq0 = NP; h = v >> 4; r0 = (v & 15) * 16; rows = 256; }
;     const int npairs = hsel < 0 ? 8 : 4; if (hsel > 0) r0 += 8;
;     const int skey = tid >> 3, sc16 = tid & 7;
;     const unsigned kdst = NA_KR + skey * 128 + 16 * (sc16 ^ (skey & 7)), vdst = NA_VR + skey * 128 + 16 * (sc16 ^ (((skey >> 1) & 3) << 1));
;     const size_t ssrc = (size_t)skey * 512 + h * 64 + 8 * sc16;
;     {
;         const int lo = na_start(r0, rows);
;         u32x4 kr[9], vr[9];
; #pragma unroll
;         for (int i = 0; i < 9; ++i) { const int row = min(lo + i, rows - 1); const size_t o = ((size_t)sq0 + (size_t)row * 64) * 512 + ssrc; kr[i] = *(const u32x4*)(KA + o); vr[i] = *(const u32x4*)(VA + o); }
; #pragma unroll
;         for (int i = 0; i < 9; ++i) { const int row = min(lo + i, rows - 1); const unsigned sl = (unsigned)(row % 9) * 8192u;
;             if (lo + i < rows) { *(LAS u32x4*)(lds + sl + kdst) = kr[i]; *(LAS u32x4*)(lds + sl + vdst) = vr[i]; } }
;         LAS float* rpbs = (LAS float*)(lds + NA_RPB);
;         for (int i = tid; i < 465; i += 512) rpbs[i] = P.rpb[h * 465 + i] * LOG2E;
;     }
;     LBAR();
;     const int rsel = wave >> 2, nb = wave & 3;
;     const int g = lane >> 4, l15 = lane & 15, q4 = l15 >> 2, p = lane & 3;
;     const int kstart = nb == 0 ? 0 : (nb == 1 ? 8 : (nb == 2 ? 24 : 32));
;     const int qc = 16 * nb + l15, wsq = min(max(qc - 8, 0), 48);
;     const LAS float* rp = (const LAS float*)(lds + NA_RPB);
;     float msk[2][4]; int bofs[2][4];
; #pragma unroll
;     for (int kt = 0; kt < 2; ++kt)
; #pragma unroll
;         for (int i = 0; i < 4; ++i) { const int kc = kstart + 16 * kt + 4 * g + i; msk[kt][i] = ((kc >= wsq) && (kc < wsq + 16)) ? -NA_SHIFT : -INFINITY; bofs[kt][i] = min(max(kc - qc + 15, 0), 30); }
; __global__ void __launch_bounds__(512, 2) mk_fwd(Params P, int ph_lo, int ph_hi) {
;     ...
;     if (IN(3)) REPS(3) {
;         unsigned* ctr = (unsigned*)(P.ws + OFF_CTL) + 64 * rep_;
;         LAS unsigned* misc = (LAS unsigned*)(lds + LDS_MISC);
;         for (;;) {
.LBB0_263:
	s_cmp_lt_i32 s28, 4
	s_cselect_b64 s[40:41], -1, 0
	s_and_b64 s[0:1], s[40:41], s[0:1]
	s_andn2_b64 vcc, exec, s[0:1]
	s_cbranch_vccnz .LBB0_326
	s_cmp_ge_u32 s97, 4
	s_cbranch_scc0 .Lp2_prio
	s_setprio 1
.Lp2_prio:
	s_add_u32 s42, s22, 0xc000000
	s_addc_u32 s43, s23, 0
	s_add_u32 s44, s22, 0x11000000
	v_lshrrev_b32_e32 v66, 3, v0
	s_addc_u32 s45, s23, 0
	v_xor_b32_e32 v2, v66, v0
	s_add_u32 s46, s22, 0x16000000
	v_and_b32_e32 v4, 7, v0
	v_lshlrev_b32_e32 v1, 7, v66
	v_lshlrev_b32_e32 v2, 4, v2
	s_movk_i32 s0, 0x70
	s_addc_u32 s47, s23, 0
	v_and_or_b32 v67, v2, s0, v1
	v_bitop3_b32 v2, v66, v4, 6 bitop3:0x6c
	s_bfe_u32 s53, s31, 0x20006
	v_and_b32_e32 v85, 15, v0
	v_lshlrev_b32_e32 v2, 4, v2
	s_mov_b32 s0, 0x12000
	s_add_i32 s4, 0, 0x24000
	s_lshr_b32 s52, s31, 8
	v_lshrrev_b32_e32 v5, 4, v180
	v_lshl_or_b32 v103, s53, 4, v85
	v_mov_b32_e32 v71, 0
	v_lshlrev_b32_e32 v3, 3, v4
	v_or3_b32 v81, v1, v2, s0
	s_cmp_eq_u32 s53, 2
	v_sub_u32_e64 v2, v103, 8 clamp
	v_lshlrev_b32_e32 v68, 3, v5
	v_mov_b32_e32 v69, v71
	v_lshl_or_b32 v79, v66, 9, v3
	v_lshl_add_u32 v83, v0, 2, s4
	s_cselect_b32 s54, 24, 32
	v_min_u32_e32 v104, 48, v2
	v_lshlrev_b32_e32 v105, 2, v5
	v_lshl_add_u64 v[2:3], s[22:23], 0, v[68:69]
	s_mov_b64 s[4:5], 0x1b000000
	v_bitop3_b32 v6, v5, v0, 7 bitop3:0x78
	v_bitop3_b32 v4, v5, v4, 4 bitop3:0x36
	s_add_u32 s55, s22, 0x2a000000
	v_lshlrev_b32_e32 v5, 4, v0
	v_lshl_add_u64 v[72:73], v[2:3], 0, s[4:5]
	s_mov_b64 s[4:5], 0x2000000
	s_addc_u32 s64, s23, 0
	s_lshl_b32 s6, s97, 1
	s_and_b32 s7, s97, 0x3fffffe
	v_and_b32_e32 v70, 0xf0, v5
	v_lshlrev_b32_e32 v10, 1, v0
	v_and_b32_e32 v102, 3, v0
	v_lshl_add_u64 v[74:75], v[2:3], 0, s[4:5]
	v_lshl_add_u64 v[2:3], s[22:23], 0, v[70:71]
	s_mov_b64 s[4:5], 0x25000000
	s_add_u32 s65, s22, 0x34000000
	v_and_b32_e32 v10, 32, v10
	v_and_b32_e32 v11, 64, v0
	v_and_b32_e32 v5, 0x70, v5
	v_lshl_add_u64 v[76:77], v[2:3], 0, s[4:5]
	s_addc_u32 s68, s23, 0
	v_bitop3_b32 v5, v10, v5, v11 bitop3:0x36
	s_and_b32 s4, s6, 2
	v_lshlrev_b32_e32 v13, 3, v102
	s_add_i32 s5, 0, 0x14000
	v_add_u32_e32 v111, 0, v5
	v_lshrrev_b32_e32 v11, 3, v180
	v_add_u32_e32 v115, s5, v5
	v_add_u32_e32 v5, s5, v13
	s_lshl_b32 s5, s4, 11
	v_bfe_u32 v87, v0, 2, 2
	v_lshlrev_b32_e32 v107, 4, v4
	v_lshlrev_b32_e32 v4, 3, v0
	v_or_b32_e32 v2, 0x600, v0
	v_and_b32_e32 v11, 2, v11
	v_lshl_or_b32 v116, v85, 7, s5
	s_or_b32 s5, s97, 1
	v_lshrrev_b32_e32 v84, 4, v2
	v_and_b32_e32 v2, 56, v4
	v_bfe_u32 v10, v0, 1, 1
	v_and_or_b32 v12, v0, 12, v11
	v_and_b32_e32 v4, 8, v4
	v_add_u32_e32 v14, 0, v13
	v_lshl_or_b32 v88, s7, 4, v105
	v_lshl_or_b32 v90, s5, 4, v105
	v_or_b32_e32 v13, v68, v87
	s_lshl_b32 s7, s7, 1
	s_lshl_b32 s5, s5, 1
	v_or_b32_e32 v3, 0x200, v0
	v_lshrrev_b32_e32 v7, 2, v0
	v_add_u32_e32 v4, 0, v4
	v_and_or_b32 v11, v66, 1, v11
	v_or_b32_e32 v15, 4, v13
	v_or_b32_e32 v16, 1, v12
	v_bitop3_b32 v17, s7, v12, v10 bitop3:0x36
	v_bitop3_b32 v12, s5, v12, v10 bitop3:0x36
	v_lshrrev_b32_e32 v78, 4, v0
	v_lshrrev_b32_e32 v80, 4, v3
	v_lshrrev_b32_e32 v86, 3, v3
	v_bfe_u32 v3, v0, 6, 2
	v_and_b32_e32 v7, 12, v7
	v_lshl_add_u32 v118, v15, 8, v4
	v_lshlrev_b32_e32 v119, 4, v17
	v_bitop3_b32 v17, s7, v16, v10 bitop3:0x36
	v_lshlrev_b32_e32 v121, 4, v12
	v_bitop3_b32 v10, s5, v16, v10 bitop3:0x36
	v_lshlrev_b32_e32 v12, 7, v15
	v_bitop3_b32 v15, s6, v11, 2 bitop3:0x6c
	v_bitop3_b32 v11, s4, v11, 1 bitop3:0x36
	v_or_b32_e32 v82, 64, v78
	v_bitop3_b32 v3, v7, v85, v3 bitop3:0x36
	v_lshl_add_u32 v117, v13, 8, v4
	v_lshlrev_b32_e32 v120, 4, v17
	v_lshlrev_b32_e32 v122, 4, v10
	v_lshlrev_b32_e32 v10, 7, v13
	v_lshlrev_b32_e32 v125, 5, v15
	v_lshlrev_b32_e32 v126, 5, v11
	v_or_b32_e32 v11, 32, v13
	v_or_b32_e32 v15, 36, v13
	v_or_b32_e32 v16, 64, v13
	v_or_b32_e32 v17, 0x44, v13
	v_or_b32_e32 v18, 0x60, v13
	v_or_b32_e32 v13, 0x64, v13
	s_movk_i32 s0, 0x1d1
	v_lshlrev_b32_e32 v69, 4, v6
	v_lshlrev_b32_e32 v6, 8, v78
	v_lshl_add_u32 v3, v3, 4, 0
	v_lshlrev_b32_e32 v7, 8, v80
	v_lshlrev_b32_e32 v8, 8, v82
	v_lshlrev_b32_e32 v9, 8, v84
	v_lshl_add_u32 v127, v11, 8, v4
	v_lshl_add_u32 v128, v15, 8, v4
	v_lshlrev_b32_e32 v11, 7, v11
	v_lshlrev_b32_e32 v15, 7, v15
	v_lshl_add_u32 v131, v16, 8, v4
	v_lshl_add_u32 v132, v17, 8, v4
	v_lshlrev_b32_e32 v16, 7, v16
	v_lshlrev_b32_e32 v17, 7, v17
	v_lshl_add_u32 v135, v18, 8, v4
	v_lshl_add_u32 v136, v13, 8, v4
	v_lshlrev_b32_e32 v4, 7, v18
	v_lshlrev_b32_e32 v13, 7, v13
	s_add_u32 s69, s22, 0x3e000000
	v_cmp_gt_u32_e64 s[0:1], s0, v0
	s_mov_b32 s49, 0
	v_add_u32_e32 v106, 16, v104
	v_or_b32_e32 v108, 4, v102
	v_or_b32_e32 v109, 8, v102
	v_or_b32_e32 v110, 12, v102
	v_xor_b32_e32 v112, 0x7f, v66
	v_xor_b32_e32 v113, 0x7f, v86
	v_lshlrev_b32_e32 v114, 7, v86
	v_mov_b32_e32 v89, v71
	v_mov_b32_e32 v91, v71
	v_add_u32_e32 v123, v14, v10
	v_add_u32_e32 v124, v14, v12
	v_add_u32_e32 v129, v14, v11
	v_add_u32_e32 v130, v14, v15
	v_add_u32_e32 v133, v14, v16
	v_add_u32_e32 v134, v14, v17
	v_add_u32_e32 v137, v14, v4
	v_add_u32_e32 v138, v14, v13
	v_add_u32_e32 v139, v5, v10
	v_add_u32_e32 v140, v5, v12
	v_add_u32_e32 v141, v5, v11
	v_add_u32_e32 v142, v5, v15
	v_add_u32_e32 v143, v5, v16
	v_add_u32_e32 v144, v5, v17
	v_add_u32_e32 v145, v5, v4
	v_add_u32_e32 v146, v5, v13
	s_addc_u32 s70, s23, 0
	s_add_i32 s71, 0, 0x25800
	s_movk_i32 s72, 0x43f
	s_mov_b64 s[50:51], 0x20000
	s_mov_b32 s24, 0x3f803f80
	s_mov_b32 s73, 0xc2fc0000
	v_lshlrev_b32_e32 v92, 1, v2
	v_mov_b32_e32 v147, 0xff800000
	v_mov_b32_e32 v148, 0xc1600000
	v_mov_b32_e32 v149, 0x42800000
	v_add_u32_e32 v150, v3, v6
	v_add_u32_e32 v151, v3, v7
	v_add_u32_e32 v152, v3, v8
	v_add_u32_e32 v153, v3, v9
	v_not_b32_e32 v154, 63
	s_branch .LBB0_268
